# attention item: RoPE table loads hoisted to the head of the key-tile trip; pooling epilogue loads de-serialized; IEEE division sequences in the queue items replaced by rcp+mul
# baseline (speedup 1.0000x reference)
.LBB0_605:
	s_or_b64 exec, exec, s[0:1]
	s_waitcnt lgkmcnt(0)
	s_barrier
	ds_read_b32 v1, v131 offset:228
	s_movk_i32 s0, 0x2ff
	s_waitcnt lgkmcnt(0)
	s_barrier
	v_cmp_lt_i32_e32 vcc, s0, v1
	v_readfirstlane_b32 s20, v1
	s_mov_b64 s[0:1], -1
	s_cbranch_vccnz .LBB0_600
	s_cmpk_gt_i32 s20, 0xff
	s_cbranch_scc0 .LBB0_702
	s_cmpk_gt_u32 s20, 0x1ff
	s_cbranch_scc0 .LBB0_612
	v_mov_b32_e32 v1, v0
	ds_read_b64 v[2:3], v131 offset:88
	s_and_b32 s0, s20, 3
	v_readlane_b32 s4, v254, 63
	s_or_b32 s10, s0, s4
	s_lshl_b32 s96, s10, 14
	s_lshl_b32 s1, s20, 5
	s_waitcnt lgkmcnt(0)
	v_readfirstlane_b32 s7, v2
	s_lshl_b64 s[4:5], s[96:97], 2
	v_lshlrev_b32_e32 v2, 2, v1
	v_readfirstlane_b32 s6, v3
	s_add_u32 s4, s7, s4
	v_and_b32_e32 v2, 0x7c, v2
	v_ashrrev_i32_e32 v3, 5, v1
	s_addc_u32 s5, s6, s5
	v_lshlrev_b32_e32 v130, 2, v2
	s_waitcnt vmcnt(9)
	v_lshlrev_b32_e32 v6, 7, v3
	v_lshl_add_u64 v[4:5], s[4:5], 0, v[130:131]
	v_ashrrev_i32_e32 v7, 31, v6
	v_lshl_add_u64 v[6:7], v[6:7], 2, v[4:5]
	s_barrier
	v_lshl_add_u32 v2, v2, 1, v212
	v_lshl_add_u32 v30, v3, 9, v130
	v_mul_u32_u24_e32 v31, 0x110, v3
	v_add_u32_e32 v31, v31, v2
	global_load_dwordx4 v[6:9], v30, s[4:5]
	s_add_u32 s4, s4, 0x2000
	s_addc_u32 s5, s5, 0
	global_load_dwordx4 v[10:13], v30, s[4:5]
	s_add_u32 s4, s4, 0x2000
	s_addc_u32 s5, s5, 0
	global_load_dwordx4 v[14:17], v30, s[4:5]
	s_add_u32 s4, s4, 0x2000
	s_addc_u32 s5, s5, 0
	global_load_dwordx4 v[18:21], v30, s[4:5]
	s_add_u32 s4, s4, 0x2000
	s_addc_u32 s5, s5, 0
	global_load_dwordx4 v[22:25], v30, s[4:5]
	s_add_u32 s4, s4, 0x2000
	s_addc_u32 s5, s5, 0
	global_load_dwordx4 v[26:29], v30, s[4:5]
	s_add_u32 s4, s4, 0x2000
	s_addc_u32 s5, s5, 0
	global_load_dwordx4 v[32:35], v30, s[4:5]
	s_add_u32 s4, s4, 0x2000
	s_addc_u32 s5, s5, 0
	global_load_dwordx4 v[36:39], v30, s[4:5]
	s_movk_i32 s6, 0x110
	s_waitcnt vmcnt(7)
	v_cvt_pk_bf16_f32 v6, v6, v7
	v_cvt_pk_bf16_f32 v7, v8, v9
	ds_write_b64 v31, v[6:7]
	s_waitcnt vmcnt(6)
	v_cvt_pk_bf16_f32 v10, v10, v11
	v_cvt_pk_bf16_f32 v11, v12, v13
	ds_write_b64 v31, v[10:11] offset:4352
	s_waitcnt vmcnt(5)
	v_cvt_pk_bf16_f32 v14, v14, v15
	v_cvt_pk_bf16_f32 v15, v16, v17
	ds_write_b64 v31, v[14:15] offset:8704
	s_waitcnt vmcnt(4)
	v_cvt_pk_bf16_f32 v18, v18, v19
	v_cvt_pk_bf16_f32 v19, v20, v21
	ds_write_b64 v31, v[18:19] offset:13056
	s_waitcnt vmcnt(3)
	v_cvt_pk_bf16_f32 v22, v22, v23
	v_cvt_pk_bf16_f32 v23, v24, v25
	ds_write_b64 v31, v[22:23] offset:17408
	s_waitcnt vmcnt(2)
	v_cvt_pk_bf16_f32 v26, v26, v27
	v_cvt_pk_bf16_f32 v27, v28, v29
	ds_write_b64 v31, v[26:27] offset:21760
	s_waitcnt vmcnt(1)
	v_cvt_pk_bf16_f32 v32, v32, v33
	v_cvt_pk_bf16_f32 v33, v34, v35
	ds_write_b64 v31, v[32:33] offset:26112
	s_waitcnt vmcnt(0)
	v_cvt_pk_bf16_f32 v36, v36, v37
	v_cvt_pk_bf16_f32 v37, v38, v39
	ds_write_b64 v31, v[36:37] offset:30464
	s_lshl_b32 s11, s0, 6
	s_and_b32 s12, s1, 0x1f80
	s_movk_i32 s13, 0x5ff
	s_mul_i32 s4, s12, 0x2200
	s_add_u32 s4, s28, s4
	s_addc_u32 s5, s29, 0
	s_lshl_b32 s6, s11, 2
	s_add_u32 s4, s4, s6
	s_addc_u32 s5, s5, 0
	v_lshrrev_b32_e32 v8, 4, v0
	v_lshlrev_b32_e32 v9, 2, v0
	v_and_b32_e32 v9, 60, v9
	v_mul_u32_u24_e32 v22, 0x2200, v8
	v_lshl_add_u32 v22, v9, 2, v22
	global_load_dwordx4 v[4:7], v22, s[4:5] offset:1024
	s_add_u32 s4, s4, 0x44000
	s_addc_u32 s5, s5, 0
	global_load_dwordx4 v[10:13], v22, s[4:5] offset:1024
	s_add_u32 s4, s4, 0x44000
	s_addc_u32 s5, s5, 0
	global_load_dwordx4 v[14:17], v22, s[4:5] offset:1024
	s_add_u32 s4, s4, 0x44000
	s_addc_u32 s5, s5, 0
	global_load_dwordx4 v[18:21], v22, s[4:5] offset:1024
	v_mul_u32_u24_e32 v23, 0x110, v9
	v_lshl_add_u32 v23, v8, 1, v23
	v_add_u32_e32 v23, s73, v23
	s_waitcnt vmcnt(3)
	v_cvt_pk_bf16_f32 v24, v4, v131
	ds_write_b16 v23, v24 offset:34816
	v_cvt_pk_bf16_f32 v24, v5, v131
	ds_write_b16 v23, v24 offset:35088
	v_cvt_pk_bf16_f32 v24, v6, v131
	ds_write_b16 v23, v24 offset:35360
	v_cvt_pk_bf16_f32 v24, v7, v131
	ds_write_b16 v23, v24 offset:35632
	s_waitcnt vmcnt(2)
	v_cvt_pk_bf16_f32 v24, v10, v131
	ds_write_b16 v23, v24 offset:34880
	v_cvt_pk_bf16_f32 v24, v11, v131
	ds_write_b16 v23, v24 offset:35152
	v_cvt_pk_bf16_f32 v24, v12, v131
	ds_write_b16 v23, v24 offset:35424
	v_cvt_pk_bf16_f32 v24, v13, v131
	ds_write_b16 v23, v24 offset:35696
	s_waitcnt vmcnt(1)
	v_cvt_pk_bf16_f32 v24, v14, v131
	ds_write_b16 v23, v24 offset:34944
	v_cvt_pk_bf16_f32 v24, v15, v131
	ds_write_b16 v23, v24 offset:35216
	v_cvt_pk_bf16_f32 v24, v16, v131
	ds_write_b16 v23, v24 offset:35488
	v_cvt_pk_bf16_f32 v24, v17, v131
	ds_write_b16 v23, v24 offset:35760
	s_waitcnt vmcnt(0)
	v_cvt_pk_bf16_f32 v24, v18, v131
	ds_write_b16 v23, v24 offset:35008
	v_cvt_pk_bf16_f32 v24, v19, v131
	ds_write_b16 v23, v24 offset:35280
	v_cvt_pk_bf16_f32 v24, v20, v131
	ds_write_b16 v23, v24 offset:35552
	v_cvt_pk_bf16_f32 v24, v21, v131
	ds_write_b16 v23, v24 offset:35824
	v_bfe_u32 v28, v1, 4, 2
	v_ashrrev_i32_e32 v2, 2, v1
	v_and_b32_e32 v7, 15, v1
	v_bfi_b32 v1, -16, v2, v1
	v_lshl_add_u32 v6, v28, 4, v212
	s_movk_i32 s4, 0x110
	v_mad_u64_u32 v[26:27], s[0:1], v1, s4, v[6:7]
	v_mad_u32_u24 v27, v7, s4, v6
	s_waitcnt lgkmcnt(0)
	s_barrier
	ds_read_b128 v[2:5], v26
	ds_read_b128 v[6:9], v27 offset:34816
	ds_read_b128 v[10:13], v27 offset:39168
	ds_read_b128 v[14:17], v27 offset:43520
	ds_read_b128 v[18:21], v27 offset:47872
	s_waitcnt lgkmcnt(3)
	v_mfma_f32_16x16x32_bf16 v[6:9], v[6:9], v[2:5], 0
	v_lshl_or_b32 v30, v28, 2, s11
	v_lshlrev_b32_e32 v130, 2, v30
	v_readlane_b32 s79, v254, 50
	s_waitcnt lgkmcnt(2)
	v_mfma_f32_16x16x32_bf16 v[10:13], v[10:13], v[2:5], 0
	s_waitcnt lgkmcnt(1)
	v_mfma_f32_16x16x32_bf16 v[14:17], v[14:17], v[2:5], 0
	s_waitcnt lgkmcnt(0)
	v_mfma_f32_16x16x32_bf16 v[2:5], v[18:21], v[2:5], 0
	ds_read_b128 v[18:21], v26 offset:64
	ds_read_b128 v[22:25], v27 offset:34880
	s_waitcnt lgkmcnt(0)
	v_mfma_f32_16x16x32_bf16 v[6:9], v[22:25], v[18:21], v[6:9]
	ds_read_b128 v[22:25], v27 offset:39232
	s_waitcnt lgkmcnt(0)
	v_mfma_f32_16x16x32_bf16 v[10:13], v[22:25], v[18:21], v[10:13]
	ds_read_b128 v[22:25], v27 offset:43584
	s_waitcnt lgkmcnt(0)
	v_mfma_f32_16x16x32_bf16 v[14:17], v[22:25], v[18:21], v[14:17]
	ds_read_b128 v[22:25], v27 offset:47936
	s_waitcnt lgkmcnt(0)
	v_mfma_f32_16x16x32_bf16 v[2:5], v[22:25], v[18:21], v[2:5]
	ds_read_b128 v[18:21], v26 offset:128
	ds_read_b128 v[22:25], v27 offset:34944
	s_waitcnt lgkmcnt(0)
	v_mfma_f32_16x16x32_bf16 v[6:9], v[22:25], v[18:21], v[6:9]
	ds_read_b128 v[22:25], v27 offset:39296
	s_waitcnt lgkmcnt(0)
	v_mfma_f32_16x16x32_bf16 v[10:13], v[22:25], v[18:21], v[10:13]
	ds_read_b128 v[22:25], v27 offset:43648
	s_waitcnt lgkmcnt(0)
	v_mfma_f32_16x16x32_bf16 v[14:17], v[22:25], v[18:21], v[14:17]
	ds_read_b128 v[22:25], v27 offset:48000
	s_waitcnt lgkmcnt(0)
	v_mfma_f32_16x16x32_bf16 v[2:5], v[22:25], v[18:21], v[2:5]
	ds_read_b128 v[18:21], v26 offset:192
	ds_read_b128 v[22:25], v27 offset:35008
	s_waitcnt lgkmcnt(0)
	v_mfma_f32_16x16x32_bf16 v[22:25], v[22:25], v[18:21], v[6:9]
	s_nop 2
	ds_read_b128 v[6:9], v27 offset:39360
	s_waitcnt lgkmcnt(0)
	v_mfma_f32_16x16x32_bf16 v[10:13], v[6:9], v[18:21], v[10:13]
	ds_read_b128 v[6:9], v27 offset:43712
	s_waitcnt lgkmcnt(0)
	v_mfma_f32_16x16x32_bf16 v[6:9], v[6:9], v[18:21], v[14:17]
	s_nop 2
	ds_read_b128 v[14:17], v27 offset:48064
	s_waitcnt lgkmcnt(0)
	v_mfma_f32_16x16x32_bf16 v[2:5], v[14:17], v[18:21], v[2:5]
	ds_read_b64 v[16:17], v131 offset:96
	v_lshl_add_u32 v18, s10, 7, v1
	v_ashrrev_i32_e32 v19, 31, v18
	v_add_u32_e32 v14, s12, v1
	v_ashrrev_i32_e32 v15, 31, v14
	s_waitcnt lgkmcnt(0)
	v_readfirstlane_b32 s0, v17
	v_readfirstlane_b32 s1, v16
	s_nop 0
	v_mov_b32_e32 v17, s0
	v_mov_b32_e32 v16, s1
	v_lshl_add_u64 v[16:17], v[18:19], 2, v[16:17]
	flat_load_dword v1, v[16:17]
	v_mov_b64_e32 v[16:17], s[28:29]
	v_mad_i64_i32 v[16:17], s[0:1], v14, s36, v[16:17]
	v_lshlrev_b64 v[14:15], 11, v[14:15]
	v_readlane_b32 s0, v253, 55
	v_lshl_add_u64 v[26:27], s[30:31], 0, v[14:15]
	v_readlane_b32 s1, v253, 56
	v_lshl_add_u64 v[16:17], v[16:17], 0, v[130:131]
	v_lshlrev_b32_e32 v130, 1, v30
	v_lshl_add_u64 v[28:29], s[0:1], 0, v[14:15]
	v_lshl_add_u64 v[14:15], v[26:27], 0, v[130:131]
	global_load_dwordx4 v[32:35], v[16:17], off
	global_load_dwordx4 v[36:39], v[16:17], off offset:64
	global_load_dwordx4 v[40:43], v[16:17], off offset:128
	global_load_dwordx4 v[44:47], v[16:17], off offset:192
	global_load_dwordx2 v[48:49], v[14:15], off
	global_load_dwordx2 v[50:51], v[14:15], off offset:32
	global_load_dwordx2 v[52:53], v[14:15], off offset:64
	global_load_dwordx2 v[54:55], v[14:15], off offset:96
	s_mov_b64 s[0:1], 0
	v_lshl_add_u64 v[18:19], v[28:29], 0, v[130:131]
	s_waitcnt vmcnt(0) lgkmcnt(0)
	v_add_f32_e32 v22, v22, v1
	v_mul_f32_e32 v22, v22, v32
	v_lshlrev_b32_e32 v56, 16, v48
	v_mul_f32_e32 v22, v22, v56
	v_add_f32_e32 v23, v23, v1
	v_mul_f32_e32 v23, v23, v33
	v_and_b32_e32 v56, 0xffff0000, v48
	v_mul_f32_e32 v23, v23, v56
	v_add_f32_e32 v24, v24, v1
	v_mul_f32_e32 v24, v24, v34
	v_lshlrev_b32_e32 v56, 16, v49
	v_mul_f32_e32 v24, v24, v56
	v_add_f32_e32 v25, v25, v1
	v_mul_f32_e32 v25, v25, v35
	v_and_b32_e32 v56, 0xffff0000, v49
	v_mul_f32_e32 v25, v25, v56
	v_cvt_pk_bf16_f32 v22, v22, v23
	v_cvt_pk_bf16_f32 v23, v24, v25
	global_store_dwordx2 v[18:19], v[22:23], off
	v_add_f32_e32 v10, v10, v1
	v_mul_f32_e32 v10, v10, v36
	v_lshlrev_b32_e32 v56, 16, v50
	v_mul_f32_e32 v10, v10, v56
	v_add_f32_e32 v11, v11, v1
	v_mul_f32_e32 v11, v11, v37
	v_and_b32_e32 v56, 0xffff0000, v50
	v_mul_f32_e32 v11, v11, v56
	v_add_f32_e32 v12, v12, v1
	v_mul_f32_e32 v12, v12, v38
	v_lshlrev_b32_e32 v56, 16, v51
	v_mul_f32_e32 v12, v12, v56
	v_add_f32_e32 v13, v13, v1
	v_mul_f32_e32 v13, v13, v39
	v_and_b32_e32 v56, 0xffff0000, v51
	v_mul_f32_e32 v13, v13, v56
	v_cvt_pk_bf16_f32 v10, v10, v11
	v_cvt_pk_bf16_f32 v11, v12, v13
	global_store_dwordx2 v[18:19], v[10:11], off offset:32
	v_add_f32_e32 v6, v6, v1
	v_mul_f32_e32 v6, v6, v40
	v_lshlrev_b32_e32 v56, 16, v52
	v_mul_f32_e32 v6, v6, v56
	v_add_f32_e32 v7, v7, v1
	v_mul_f32_e32 v7, v7, v41
	v_and_b32_e32 v56, 0xffff0000, v52
	v_mul_f32_e32 v7, v7, v56
	v_add_f32_e32 v8, v8, v1
	v_mul_f32_e32 v8, v8, v42
	v_lshlrev_b32_e32 v56, 16, v53
	v_mul_f32_e32 v8, v8, v56
	v_add_f32_e32 v9, v9, v1
	v_mul_f32_e32 v9, v9, v43
	v_and_b32_e32 v56, 0xffff0000, v53
	v_mul_f32_e32 v9, v9, v56
	v_cvt_pk_bf16_f32 v6, v6, v7
	v_cvt_pk_bf16_f32 v7, v8, v9
	global_store_dwordx2 v[18:19], v[6:7], off offset:64
	v_add_f32_e32 v2, v2, v1
	v_mul_f32_e32 v2, v2, v44
	v_lshlrev_b32_e32 v56, 16, v54
	v_mul_f32_e32 v2, v2, v56
	v_add_f32_e32 v3, v3, v1
	v_mul_f32_e32 v3, v3, v45
	v_and_b32_e32 v56, 0xffff0000, v54
	v_mul_f32_e32 v3, v3, v56
	v_add_f32_e32 v4, v4, v1
	v_mul_f32_e32 v4, v4, v46
	v_lshlrev_b32_e32 v56, 16, v55
	v_mul_f32_e32 v4, v4, v56
	v_add_f32_e32 v5, v5, v1
	v_mul_f32_e32 v5, v5, v47
	v_and_b32_e32 v56, 0xffff0000, v55
	v_mul_f32_e32 v5, v5, v56
	v_cvt_pk_bf16_f32 v2, v2, v3
	v_cvt_pk_bf16_f32 v3, v4, v5
	global_store_dwordx2 v[18:19], v[2:3], off offset:96
	s_nop 0
	s_nop 0
	s_nop 0
	s_nop 0
	s_nop 0
	s_nop 0
	s_nop 0
	s_nop 0
	s_nop 1
	s_nop 0
	s_nop 0
	s_nop 0
	s_nop 0
	s_nop 0
	s_nop 0
	s_nop 1
	s_nop 0
	s_nop 0
	s_nop 0
	s_nop 0
	s_nop 0
	s_nop 0
	s_nop 1
	s_nop 0
	s_nop 0
	s_nop 0
	s_nop 1
	s_nop 0

.LBB0_641:
	s_or_b64 exec, exec, s[0:1]
	v_sub_u32_e32 v9, v10, v9
	v_cvt_f32_i32_e32 v9, v9
	v_lshl_add_u32 v2, v2, 1, v212
	s_nop 1
	s_movk_i32 s0, 0x210
	s_nop 7
	v_rcp_f32_e32 v10, v9
	s_nop 0
	v_mul_f32_e32 v8, v8, v10
	v_lshlrev_b32_e32 v9, 10, v7
	v_add3_u32 v9, s73, v9, v3
	ds_read_b32 v9, v9 offset:8192
	v_or_b32_e32 v10, 1, v7
	s_waitcnt lgkmcnt(0)
	v_sub_f32_e32 v8, v8, v9
	v_cvt_pk_bf16_f32 v9, v8, v131
	v_mul_lo_u32 v8, v7, s0
	v_add_u32_e32 v8, v2, v8
	ds_write_b16 v8, v9 offset:49152
	v_add_u32_e32 v9, v6, v10
	v_add_u32_e32 v12, v9, v4
	v_max_i32_e32 v11, 0, v9
	v_min_i32_e32 v12, s23, v12
	v_cmp_gt_i32_e32 vcc, v12, v11
	v_mov_b32_e32 v9, 0
	s_and_saveexec_b64 s[0:1], vcc
	s_cbranch_execz .LBB0_645
	v_lshl_or_b32 v9, v11, 10, v3
	s_lshl_b32 s4, s22, 10
	v_subrev_u32_e32 v9, s4, v9
	s_add_i32 s4, s73, 0x2000
	v_add_u32_e32 v13, s4, v9
	v_mov_b32_e32 v9, 0
	s_mov_b64 s[4:5], 0
	v_mov_b32_e32 v14, v11

.LBB0_645:
	s_or_b64 exec, exec, s[0:1]
	v_sub_u32_e32 v11, v12, v11
	v_cvt_f32_i32_e32 v11, v11
	v_lshlrev_b32_e32 v10, 10, v10
	v_add3_u32 v10, s73, v10, v3
	ds_read_b32 v10, v10 offset:8192
	s_nop 7
	v_rcp_f32_e32 v12, v11
	s_nop 0
	v_mul_f32_e32 v9, v9, v12
	s_waitcnt lgkmcnt(0)
	v_sub_f32_e32 v9, v9, v10
	v_cvt_pk_bf16_f32 v9, v9, v131
	v_or_b32_e32 v10, 2, v7
	ds_write_b16 v8, v9 offset:49680
	v_add_u32_e32 v9, v6, v10
	v_add_u32_e32 v12, v9, v4
	v_max_i32_e32 v11, 0, v9
	v_min_i32_e32 v12, s23, v12
	v_cmp_gt_i32_e32 vcc, v12, v11
	v_mov_b32_e32 v9, 0
	s_and_saveexec_b64 s[0:1], vcc
	s_cbranch_execz .LBB0_649
	v_lshl_or_b32 v9, v11, 10, v3
	s_lshl_b32 s4, s22, 10
	v_subrev_u32_e32 v9, s4, v9
	s_add_i32 s4, s73, 0x2000
	v_add_u32_e32 v13, s4, v9
	v_mov_b32_e32 v9, 0
	s_mov_b64 s[4:5], 0
	v_mov_b32_e32 v14, v11

.LBB0_649:
	s_or_b64 exec, exec, s[0:1]
	v_sub_u32_e32 v11, v12, v11
	v_cvt_f32_i32_e32 v11, v11
	v_lshlrev_b32_e32 v10, 10, v10
	v_add3_u32 v10, s73, v10, v3
	ds_read_b32 v10, v10 offset:8192
	s_nop 7
	v_rcp_f32_e32 v12, v11
	s_nop 0
	v_mul_f32_e32 v9, v9, v12
	s_waitcnt lgkmcnt(0)
	v_sub_f32_e32 v9, v9, v10
	v_cvt_pk_bf16_f32 v9, v9, v131
	v_or_b32_e32 v10, 3, v7
	ds_write_b16 v8, v9 offset:50208
	v_add_u32_e32 v9, v6, v10
	v_add_u32_e32 v12, v9, v4
	v_max_i32_e32 v11, 0, v9
	v_min_i32_e32 v12, s23, v12
	v_cmp_gt_i32_e32 vcc, v12, v11
	v_mov_b32_e32 v9, 0
	s_and_saveexec_b64 s[0:1], vcc
	s_cbranch_execz .LBB0_653
	v_lshl_or_b32 v9, v11, 10, v3
	s_lshl_b32 s4, s22, 10
	v_subrev_u32_e32 v9, s4, v9
	s_add_i32 s4, s73, 0x2000
	v_add_u32_e32 v13, s4, v9
	v_mov_b32_e32 v9, 0
	s_mov_b64 s[4:5], 0
	v_mov_b32_e32 v14, v11

.LBB0_653:
	s_or_b64 exec, exec, s[0:1]
	v_sub_u32_e32 v11, v12, v11
	v_cvt_f32_i32_e32 v11, v11
	v_lshlrev_b32_e32 v10, 10, v10
	v_add3_u32 v10, s73, v10, v3
	ds_read_b32 v10, v10 offset:8192
	s_nop 7
	v_rcp_f32_e32 v12, v11
	s_nop 0
	v_mul_f32_e32 v9, v9, v12
	s_waitcnt lgkmcnt(0)
	v_sub_f32_e32 v9, v9, v10
	v_cvt_pk_bf16_f32 v9, v9, v131
	v_or_b32_e32 v10, 4, v7
	ds_write_b16 v8, v9 offset:50736
	v_add_u32_e32 v9, v6, v10
	v_add_u32_e32 v12, v9, v4
	v_max_i32_e32 v11, 0, v9
	v_min_i32_e32 v12, s23, v12
	v_cmp_gt_i32_e32 vcc, v12, v11
	v_mov_b32_e32 v9, 0
	s_and_saveexec_b64 s[0:1], vcc
	s_cbranch_execz .LBB0_657
	v_lshl_or_b32 v9, v11, 10, v3
	s_lshl_b32 s4, s22, 10
	v_subrev_u32_e32 v9, s4, v9
	s_add_i32 s4, s73, 0x2000
	v_add_u32_e32 v13, s4, v9
	v_mov_b32_e32 v9, 0
	s_mov_b64 s[4:5], 0
	v_mov_b32_e32 v14, v11

.LBB0_657:
	s_or_b64 exec, exec, s[0:1]
	v_sub_u32_e32 v11, v12, v11
	v_cvt_f32_i32_e32 v11, v11
	v_lshlrev_b32_e32 v10, 10, v10
	v_add3_u32 v10, s73, v10, v3
	ds_read_b32 v10, v10 offset:8192
	s_nop 7
	v_rcp_f32_e32 v12, v11
	s_nop 0
	v_mul_f32_e32 v9, v9, v12
	s_waitcnt lgkmcnt(0)
	v_sub_f32_e32 v9, v9, v10
	v_cvt_pk_bf16_f32 v9, v9, v131
	v_or_b32_e32 v10, 5, v7
	ds_write_b16 v8, v9 offset:51264
	v_add_u32_e32 v9, v6, v10
	v_add_u32_e32 v12, v9, v4
	v_max_i32_e32 v11, 0, v9
	v_min_i32_e32 v12, s23, v12
	v_cmp_gt_i32_e32 vcc, v12, v11
	v_mov_b32_e32 v9, 0
	s_and_saveexec_b64 s[0:1], vcc
	s_cbranch_execz .LBB0_661
	v_lshl_or_b32 v9, v11, 10, v3
	s_lshl_b32 s4, s22, 10
	v_subrev_u32_e32 v9, s4, v9
	s_add_i32 s4, s73, 0x2000
	v_add_u32_e32 v13, s4, v9
	v_mov_b32_e32 v9, 0
	s_mov_b64 s[4:5], 0
	v_mov_b32_e32 v14, v11

.LBB0_661:
	s_or_b64 exec, exec, s[0:1]
	v_sub_u32_e32 v11, v12, v11
	v_cvt_f32_i32_e32 v11, v11
	v_lshlrev_b32_e32 v10, 10, v10
	v_add3_u32 v10, s73, v10, v3
	ds_read_b32 v10, v10 offset:8192
	s_nop 7
	v_rcp_f32_e32 v12, v11
	s_nop 0
	v_mul_f32_e32 v9, v9, v12
	s_waitcnt lgkmcnt(0)
	v_sub_f32_e32 v9, v9, v10
	v_cvt_pk_bf16_f32 v9, v9, v131
	v_or_b32_e32 v10, 6, v7
	ds_write_b16 v8, v9 offset:51792
	v_add_u32_e32 v9, v6, v10
	v_add_u32_e32 v12, v9, v4
	v_max_i32_e32 v11, 0, v9
	v_min_i32_e32 v12, s23, v12
	v_cmp_gt_i32_e32 vcc, v12, v11
	v_mov_b32_e32 v9, 0
	s_and_saveexec_b64 s[0:1], vcc
	s_cbranch_execz .LBB0_665
	v_lshl_or_b32 v9, v11, 10, v3
	s_lshl_b32 s4, s22, 10
	v_subrev_u32_e32 v9, s4, v9
	s_add_i32 s4, s73, 0x2000
	v_add_u32_e32 v13, s4, v9
	v_mov_b32_e32 v9, 0
	s_mov_b64 s[4:5], 0
	v_mov_b32_e32 v14, v11

.LBB0_665:
	s_or_b64 exec, exec, s[0:1]
	v_sub_u32_e32 v11, v12, v11
	v_cvt_f32_i32_e32 v11, v11
	v_lshlrev_b32_e32 v10, 10, v10
	v_add3_u32 v10, s73, v10, v3
	ds_read_b32 v10, v10 offset:8192
	s_nop 7
	v_rcp_f32_e32 v12, v11
	s_nop 0
	v_mul_f32_e32 v9, v9, v12
	s_waitcnt lgkmcnt(0)
	v_sub_f32_e32 v9, v9, v10
	v_cvt_pk_bf16_f32 v9, v9, v131
	v_or_b32_e32 v10, 7, v7
	ds_write_b16 v8, v9 offset:52320
	v_add_u32_e32 v9, v6, v10
	v_add_u32_e32 v12, v9, v4
	v_max_i32_e32 v11, 0, v9
	v_min_i32_e32 v12, s23, v12
	v_cmp_gt_i32_e32 vcc, v12, v11
	v_mov_b32_e32 v9, 0
	s_and_saveexec_b64 s[0:1], vcc
	s_cbranch_execz .LBB0_669
	v_lshl_or_b32 v9, v11, 10, v3
	s_lshl_b32 s4, s22, 10
	v_subrev_u32_e32 v9, s4, v9
	s_add_i32 s4, s73, 0x2000
	v_add_u32_e32 v13, s4, v9
	v_mov_b32_e32 v9, 0
	s_mov_b64 s[4:5], 0
	v_mov_b32_e32 v14, v11

.LBB0_669:
	s_or_b64 exec, exec, s[0:1]
	v_sub_u32_e32 v11, v12, v11
	v_cvt_f32_i32_e32 v11, v11
	v_lshlrev_b32_e32 v10, 10, v10
	v_add3_u32 v10, s73, v10, v3
	ds_read_b32 v10, v10 offset:8192
	s_nop 7
	v_rcp_f32_e32 v12, v11
	s_nop 0
	v_mul_f32_e32 v9, v9, v12
	s_waitcnt lgkmcnt(0)
	v_sub_f32_e32 v9, v9, v10
	v_cvt_pk_bf16_f32 v9, v9, v131
	v_or_b32_e32 v10, 8, v7
	ds_write_b16 v8, v9 offset:52848
	v_add_u32_e32 v9, v6, v10
	v_add_u32_e32 v12, v9, v4
	v_max_i32_e32 v11, 0, v9
	v_min_i32_e32 v12, s23, v12
	v_cmp_gt_i32_e32 vcc, v12, v11
	v_mov_b32_e32 v9, 0
	s_and_saveexec_b64 s[0:1], vcc
	s_cbranch_execz .LBB0_673
	v_lshl_or_b32 v9, v11, 10, v3
	s_lshl_b32 s4, s22, 10
	v_subrev_u32_e32 v9, s4, v9
	s_add_i32 s4, s73, 0x2000
	v_add_u32_e32 v13, s4, v9
	v_mov_b32_e32 v9, 0
	s_mov_b64 s[4:5], 0
	v_mov_b32_e32 v14, v11

.LBB0_673:
	s_or_b64 exec, exec, s[0:1]
	v_sub_u32_e32 v11, v12, v11
	v_cvt_f32_i32_e32 v11, v11
	v_lshlrev_b32_e32 v10, 10, v10
	v_add3_u32 v10, s73, v10, v3
	ds_read_b32 v10, v10 offset:8192
	s_nop 7
	v_rcp_f32_e32 v12, v11
	s_nop 0
	v_mul_f32_e32 v9, v9, v12
	s_waitcnt lgkmcnt(0)
	v_sub_f32_e32 v9, v9, v10
	v_cvt_pk_bf16_f32 v9, v9, v131
	v_or_b32_e32 v10, 9, v7
	ds_write_b16 v8, v9 offset:53376
	v_add_u32_e32 v9, v6, v10
	v_add_u32_e32 v12, v9, v4
	v_max_i32_e32 v11, 0, v9
	v_min_i32_e32 v12, s23, v12
	v_cmp_gt_i32_e32 vcc, v12, v11
	v_mov_b32_e32 v9, 0
	s_and_saveexec_b64 s[0:1], vcc
	s_cbranch_execz .LBB0_677
	v_lshl_or_b32 v9, v11, 10, v3
	s_lshl_b32 s4, s22, 10
	v_subrev_u32_e32 v9, s4, v9
	s_add_i32 s4, s73, 0x2000
	v_add_u32_e32 v13, s4, v9
	v_mov_b32_e32 v9, 0
	s_mov_b64 s[4:5], 0
	v_mov_b32_e32 v14, v11

.LBB0_677:
	s_or_b64 exec, exec, s[0:1]
	v_sub_u32_e32 v11, v12, v11
	v_cvt_f32_i32_e32 v11, v11
	v_lshlrev_b32_e32 v10, 10, v10
	v_add3_u32 v10, s73, v10, v3
	ds_read_b32 v10, v10 offset:8192
	s_nop 7
	v_rcp_f32_e32 v12, v11
	s_nop 0
	v_mul_f32_e32 v9, v9, v12
	s_waitcnt lgkmcnt(0)
	v_sub_f32_e32 v9, v9, v10
	v_cvt_pk_bf16_f32 v9, v9, v131
	v_or_b32_e32 v10, 10, v7
	ds_write_b16 v8, v9 offset:53904
	v_add_u32_e32 v9, v6, v10
	v_add_u32_e32 v12, v9, v4
	v_max_i32_e32 v11, 0, v9
	v_min_i32_e32 v12, s23, v12
	v_cmp_gt_i32_e32 vcc, v12, v11
	v_mov_b32_e32 v9, 0
	s_and_saveexec_b64 s[0:1], vcc
	s_cbranch_execz .LBB0_681
	v_lshl_or_b32 v9, v11, 10, v3
	s_lshl_b32 s4, s22, 10
	v_subrev_u32_e32 v9, s4, v9
	s_add_i32 s4, s73, 0x2000
	v_add_u32_e32 v13, s4, v9
	v_mov_b32_e32 v9, 0
	s_mov_b64 s[4:5], 0
	v_mov_b32_e32 v14, v11

.LBB0_681:
	s_or_b64 exec, exec, s[0:1]
	v_sub_u32_e32 v11, v12, v11
	v_cvt_f32_i32_e32 v11, v11
	v_lshlrev_b32_e32 v10, 10, v10
	v_add3_u32 v10, s73, v10, v3
	ds_read_b32 v10, v10 offset:8192
	s_nop 7
	v_rcp_f32_e32 v12, v11
	s_nop 0
	v_mul_f32_e32 v9, v9, v12
	s_waitcnt lgkmcnt(0)
	v_sub_f32_e32 v9, v9, v10
	v_cvt_pk_bf16_f32 v9, v9, v131
	v_or_b32_e32 v10, 11, v7
	ds_write_b16 v8, v9 offset:54432
	v_add_u32_e32 v9, v6, v10
	v_add_u32_e32 v12, v9, v4
	v_max_i32_e32 v11, 0, v9
	v_min_i32_e32 v12, s23, v12
	v_cmp_gt_i32_e32 vcc, v12, v11
	v_mov_b32_e32 v9, 0
	s_and_saveexec_b64 s[0:1], vcc
	s_cbranch_execz .LBB0_685
	v_lshl_or_b32 v9, v11, 10, v3
	s_lshl_b32 s4, s22, 10
	v_subrev_u32_e32 v9, s4, v9
	s_add_i32 s4, s73, 0x2000
	v_add_u32_e32 v13, s4, v9
	v_mov_b32_e32 v9, 0
	s_mov_b64 s[4:5], 0
	v_mov_b32_e32 v14, v11

.LBB0_685:
	s_or_b64 exec, exec, s[0:1]
	v_sub_u32_e32 v11, v12, v11
	v_cvt_f32_i32_e32 v11, v11
	v_lshlrev_b32_e32 v10, 10, v10
	v_add3_u32 v10, s73, v10, v3
	ds_read_b32 v10, v10 offset:8192
	s_nop 7
	v_rcp_f32_e32 v12, v11
	s_nop 0
	v_mul_f32_e32 v9, v9, v12
	s_waitcnt lgkmcnt(0)
	v_sub_f32_e32 v9, v9, v10
	v_cvt_pk_bf16_f32 v9, v9, v131
	v_or_b32_e32 v10, 12, v7
	ds_write_b16 v8, v9 offset:54960
	v_add_u32_e32 v9, v6, v10
	v_add_u32_e32 v12, v9, v4
	v_max_i32_e32 v11, 0, v9
	v_min_i32_e32 v12, s23, v12
	v_cmp_gt_i32_e32 vcc, v12, v11
	v_mov_b32_e32 v9, 0
	s_and_saveexec_b64 s[0:1], vcc
	s_cbranch_execz .LBB0_689
	v_lshl_or_b32 v9, v11, 10, v3
	s_lshl_b32 s4, s22, 10
	v_subrev_u32_e32 v9, s4, v9
	s_add_i32 s4, s73, 0x2000
	v_add_u32_e32 v13, s4, v9
	v_mov_b32_e32 v9, 0
	s_mov_b64 s[4:5], 0
	v_mov_b32_e32 v14, v11

.LBB0_689:
	s_or_b64 exec, exec, s[0:1]
	v_sub_u32_e32 v11, v12, v11
	v_cvt_f32_i32_e32 v11, v11
	v_lshlrev_b32_e32 v10, 10, v10
	v_add3_u32 v10, s73, v10, v3
	ds_read_b32 v10, v10 offset:8192
	s_nop 7
	v_rcp_f32_e32 v12, v11
	s_nop 0
	v_mul_f32_e32 v9, v9, v12
	s_waitcnt lgkmcnt(0)
	v_sub_f32_e32 v9, v9, v10
	v_cvt_pk_bf16_f32 v9, v9, v131
	v_or_b32_e32 v10, 13, v7
	ds_write_b16 v8, v9 offset:55488
	v_add_u32_e32 v9, v6, v10
	v_add_u32_e32 v12, v9, v4
	v_max_i32_e32 v11, 0, v9
	v_min_i32_e32 v12, s23, v12
	v_cmp_gt_i32_e32 vcc, v12, v11
	v_mov_b32_e32 v9, 0
	s_and_saveexec_b64 s[0:1], vcc
	s_cbranch_execz .LBB0_693
	v_lshl_or_b32 v9, v11, 10, v3
	s_lshl_b32 s4, s22, 10
	v_subrev_u32_e32 v9, s4, v9
	s_add_i32 s4, s73, 0x2000
	v_add_u32_e32 v13, s4, v9
	v_mov_b32_e32 v9, 0
	s_mov_b64 s[4:5], 0
	v_mov_b32_e32 v14, v11

.LBB0_693:
	s_or_b64 exec, exec, s[0:1]
	v_sub_u32_e32 v11, v12, v11
	v_cvt_f32_i32_e32 v11, v11
	v_lshlrev_b32_e32 v10, 10, v10
	v_add3_u32 v10, s73, v10, v3
	ds_read_b32 v10, v10 offset:8192
	s_nop 7
	v_rcp_f32_e32 v12, v11
	s_nop 0
	v_mul_f32_e32 v9, v9, v12
	s_waitcnt lgkmcnt(0)
	v_sub_f32_e32 v9, v9, v10
	v_cvt_pk_bf16_f32 v9, v9, v131
	ds_write_b16 v8, v9 offset:56016
	v_or_b32_e32 v9, 14, v7
	v_add_u32_e32 v7, v6, v9
	v_add_u32_e32 v11, v7, v4
	v_max_i32_e32 v10, 0, v7
	v_min_i32_e32 v11, s23, v11
	v_cmp_gt_i32_e32 vcc, v11, v10
	v_mov_b32_e32 v7, 0
	s_and_saveexec_b64 s[0:1], vcc
	s_cbranch_execz .LBB0_697
	v_lshl_or_b32 v7, v10, 10, v3
	s_lshl_b32 s4, s22, 10
	v_subrev_u32_e32 v7, s4, v7
	s_add_i32 s4, s73, 0x2000
	v_add_u32_e32 v12, s4, v7
	v_mov_b32_e32 v7, 0
	s_mov_b64 s[4:5], 0
	v_mov_b32_e32 v13, v10

.LBB0_697:
	s_or_b64 exec, exec, s[0:1]
	v_sub_u32_e32 v10, v11, v10
	v_cvt_f32_i32_e32 v10, v10
	v_lshlrev_b32_e32 v9, 10, v9
	v_add3_u32 v9, s73, v9, v3
	ds_read_b32 v9, v9 offset:8192
	s_nop 2
	v_or_b32_e32 v5, 15, v5
	s_nop 6
	v_rcp_f32_e32 v11, v10
	s_nop 0
	v_mul_f32_e32 v7, v7, v11
	s_waitcnt lgkmcnt(0)
	v_sub_f32_e32 v7, v7, v9
	v_add_u32_e32 v6, v6, v5
	v_cvt_pk_bf16_f32 v7, v7, v131
	v_add_u32_e32 v4, v6, v4
	ds_write_b16 v8, v7 offset:56544
	v_max_i32_e32 v6, 0, v6
	v_min_i32_e32 v7, s23, v4
	v_cmp_gt_i32_e32 vcc, v7, v6
	v_mov_b32_e32 v4, 0
	s_and_saveexec_b64 s[0:1], vcc
	s_cbranch_execz .LBB0_701
	v_lshl_or_b32 v4, v6, 10, v3
	s_lshl_b32 s4, s22, 10
	v_subrev_u32_e32 v4, s4, v4
	s_add_i32 s4, s73, 0x2000
	v_add_u32_e32 v8, s4, v4
	v_mov_b32_e32 v4, 0
	s_mov_b64 s[4:5], 0
	v_mov_b32_e32 v9, v6

.LBB0_701:
	s_or_b64 exec, exec, s[0:1]
	v_sub_u32_e32 v6, v7, v6
	v_cvt_f32_i32_e32 v6, v6
	s_movk_i32 s4, 0x210
	v_bfe_u32 v26, v1, 4, 2
	s_nop 1
	s_nop 0
	s_nop 7
	v_rcp_f32_e32 v7, v6
	s_nop 0
	v_mul_f32_e32 v4, v4, v7
	v_lshlrev_b32_e32 v6, 10, v5
	v_add3_u32 v3, s73, v6, v3
	ds_read_b32 v3, v3 offset:8192
	v_lshlrev_b32_e32 v6, 4, v26
	s_waitcnt lgkmcnt(0)
	v_sub_f32_e32 v3, v4, v3
	v_cvt_pk_bf16_f32 v4, v3, v131
	v_mad_u64_u32 v[2:3], s[0:1], v5, s4, v[2:3]
	ds_write_b16 v2, v4 offset:49152
	v_and_b32_e32 v2, 15, v1
	v_lshrrev_b32_e32 v3, 2, v1
	v_ashrrev_i32_e32 v1, 1, v1
	v_and_b32_e32 v1, 0xffffffc0, v1
	v_and_or_b32 v27, v3, 16, v2
	v_or_b32_e32 v2, v1, v2
	v_mad_u32_u24 v3, v27, s4, v212
	v_lshlrev_b32_e32 v4, 1, v1
	v_mul_lo_u32 v7, v2, s62
	v_add3_u32 v22, v3, v4, v6
	v_add3_u32 v28, s79, v6, v7
	s_waitcnt lgkmcnt(0)
	s_barrier
	ds_read_b128 v[2:5], v22 offset:49152
	ds_read_b128 v[6:9], v28
	ds_read_b128 v[10:13], v28 offset:2304
	ds_read_b128 v[14:17], v28 offset:4608
	ds_read_b128 v[18:21], v28 offset:6912
	s_waitcnt lgkmcnt(3)
	v_mfma_f32_16x16x32_bf16 v[6:9], v[6:9], v[2:5], 0
	s_mov_b64 s[0:1], 0x78a3d00
	s_waitcnt lgkmcnt(2)
	v_mfma_f32_16x16x32_bf16 v[10:13], v[10:13], v[2:5], 0
	s_waitcnt lgkmcnt(1)
	v_mfma_f32_16x16x32_bf16 v[14:17], v[14:17], v[2:5], 0
	s_waitcnt lgkmcnt(0)
	v_mfma_f32_16x16x32_bf16 v[2:5], v[18:21], v[2:5], 0
	ds_read_b128 v[18:21], v22 offset:49216
	ds_read_b128 v[22:25], v28 offset:64
	s_waitcnt lgkmcnt(0)
	v_mfma_f32_16x16x32_bf16 v[22:25], v[22:25], v[18:21], v[6:9]
	s_nop 2
	ds_read_b128 v[6:9], v28 offset:2368
	s_waitcnt lgkmcnt(0)
	v_mfma_f32_16x16x32_bf16 v[10:13], v[6:9], v[18:21], v[10:13]
	ds_read_b128 v[6:9], v28 offset:4672
	s_waitcnt lgkmcnt(0)
	v_mfma_f32_16x16x32_bf16 v[6:9], v[6:9], v[18:21], v[14:17]
	s_nop 2
	ds_read_b128 v[14:17], v28 offset:6976
	s_waitcnt lgkmcnt(0)
	v_mfma_f32_16x16x32_bf16 v[2:5], v[14:17], v[18:21], v[2:5]
	ds_read_b64 v[20:21], v131 offset:192
	v_or_b32_e32 v14, s21, v27
	v_lshlrev_b32_e32 v130, 11, v14
	v_lshl_add_u64 v[14:15], s[18:19], 0, v[130:131]
	v_lshl_add_u64 v[16:17], v[14:15], 0, s[0:1]
	s_mov_b64 s[0:1], 0xe0c3d00
	v_lshl_or_b32 v18, v26, 2, v1
	v_lshl_add_u64 v[14:15], v[14:15], 0, s[0:1]
	s_waitcnt lgkmcnt(0)
	v_readfirstlane_b32 s0, v20
	v_readfirstlane_b32 s1, v21
	s_add_u32 s0, s0, s94
	v_ashrrev_i32_e32 v19, 31, v18
	s_addc_u32 s1, s1, s95
	v_lshlrev_b64 v[20:21], 2, v[18:19]
	v_lshlrev_b64 v[30:31], 1, v[18:19]
	v_lshl_add_u64 v[26:27], s[0:1], 0, v[20:21]
	v_lshl_add_u64 v[32:33], v[16:17], 0, v[30:31]
	global_load_dwordx4 v[34:37], v[26:27], off
	global_load_dwordx4 v[38:41], v[26:27], off offset:64
	global_load_dwordx4 v[42:45], v[26:27], off offset:128
	global_load_dwordx4 v[46:49], v[26:27], off offset:192
	global_load_dwordx2 v[50:51], v[32:33], off
	global_load_dwordx2 v[52:53], v[32:33], off offset:32
	global_load_dwordx2 v[54:55], v[32:33], off offset:64
	global_load_dwordx2 v[56:57], v[32:33], off offset:96
	v_lshl_add_u64 v[58:59], v[14:15], 0, v[30:31]
	s_waitcnt vmcnt(0) lgkmcnt(0)
	v_mul_f32_e32 v22, v22, v34
	v_lshlrev_b32_e32 v60, 16, v50
	v_mul_f32_e32 v22, v22, v60
	v_mul_f32_e32 v23, v23, v35
	v_and_b32_e32 v60, 0xffff0000, v50
	v_mul_f32_e32 v23, v23, v60
	v_mul_f32_e32 v24, v24, v36
	v_lshlrev_b32_e32 v60, 16, v51
	v_mul_f32_e32 v24, v24, v60
	v_mul_f32_e32 v25, v25, v37
	v_and_b32_e32 v60, 0xffff0000, v51
	v_mul_f32_e32 v25, v25, v60
	v_cvt_pk_bf16_f32 v22, v22, v23
	v_cvt_pk_bf16_f32 v23, v24, v25
	global_store_dwordx2 v[58:59], v[22:23], off
	v_mul_f32_e32 v10, v10, v38
	v_lshlrev_b32_e32 v60, 16, v52
	v_mul_f32_e32 v10, v10, v60
	v_mul_f32_e32 v11, v11, v39
	v_and_b32_e32 v60, 0xffff0000, v52
	v_mul_f32_e32 v11, v11, v60
	v_mul_f32_e32 v12, v12, v40
	v_lshlrev_b32_e32 v60, 16, v53
	v_mul_f32_e32 v12, v12, v60
	v_mul_f32_e32 v13, v13, v41
	v_and_b32_e32 v60, 0xffff0000, v53
	v_mul_f32_e32 v13, v13, v60
	v_cvt_pk_bf16_f32 v10, v10, v11
	v_cvt_pk_bf16_f32 v11, v12, v13
	global_store_dwordx2 v[58:59], v[10:11], off offset:32
	v_mul_f32_e32 v6, v6, v42
	v_lshlrev_b32_e32 v60, 16, v54
	v_mul_f32_e32 v6, v6, v60
	v_mul_f32_e32 v7, v7, v43
	v_and_b32_e32 v60, 0xffff0000, v54
	v_mul_f32_e32 v7, v7, v60
	v_mul_f32_e32 v8, v8, v44
	v_lshlrev_b32_e32 v60, 16, v55
	v_mul_f32_e32 v8, v8, v60
	v_mul_f32_e32 v9, v9, v45
	v_and_b32_e32 v60, 0xffff0000, v55
	v_mul_f32_e32 v9, v9, v60
	v_cvt_pk_bf16_f32 v6, v6, v7
	v_cvt_pk_bf16_f32 v7, v8, v9
	global_store_dwordx2 v[58:59], v[6:7], off offset:64
	v_mul_f32_e32 v2, v2, v46
	v_lshlrev_b32_e32 v60, 16, v56
	v_mul_f32_e32 v2, v2, v60
	v_mul_f32_e32 v3, v3, v47
	v_and_b32_e32 v60, 0xffff0000, v56
	v_mul_f32_e32 v3, v3, v60
	v_mul_f32_e32 v4, v4, v48
	v_lshlrev_b32_e32 v60, 16, v57
	v_mul_f32_e32 v4, v4, v60
	v_mul_f32_e32 v5, v5, v49
	v_and_b32_e32 v60, 0xffff0000, v57
	v_mul_f32_e32 v5, v5, v60
	v_cvt_pk_bf16_f32 v2, v2, v3
	v_cvt_pk_bf16_f32 v3, v4, v5
	global_store_dwordx2 v[58:59], v[2:3], off offset:96
	s_mov_b64 s[0:1], 0
	s_nop 0
	s_nop 1
	s_nop 0
	s_nop 0
	s_nop 1
	s_nop 0
	s_nop 0
	s_nop 1
	s_nop 0
	s_nop 0
	s_nop 1
	s_nop 0
	s_nop 0
	s_nop 1
	s_nop 0
	s_nop 0
	s_nop 1
	s_nop 0
	s_nop 0
	s_nop 1
	s_nop 0
	s_nop 0
	s_nop 1
	s_nop 0

.LBB0_724:
	v_cndmask_b32_e64 v58, 0, 1, s[84:85]
	v_cmp_ne_u32_e64 s[6:7], 1, v58
	s_andn2_b64 vcc, exec, s[84:85]
	s_cbranch_vccnz .Lat_norope
	v_add_u32_e32 v136, s64, v90
	v_and_b32_e32 v137, 63, v136
	v_ashrrev_i32_e32 v136, 6, v136
	v_cndmask_b32_e64 v136, v137, v136, s[4:5]
	v_lshl_or_b32 v136, v136, 4, v92
	v_ashrrev_i32_e32 v137, 31, v136
	v_lshl_add_u64 v[136:137], v[136:137], 3, s[88:89]
	global_load_dwordx4 v[138:141], v[136:137], off offset:16
	global_load_dwordx4 v[142:145], v[136:137], off
	v_add_u32_e32 v154, s64, v94
	v_and_b32_e32 v155, 63, v154
	v_ashrrev_i32_e32 v154, 6, v154
	v_cndmask_b32_e64 v154, v155, v154, s[4:5]
	v_lshl_or_b32 v154, v154, 4, v92
	v_ashrrev_i32_e32 v155, 31, v154
	v_lshl_add_u64 v[154:155], v[154:155], 3, s[88:89]
	global_load_dwordx4 v[146:149], v[154:155], off offset:16
	global_load_dwordx4 v[150:153], v[154:155], off
.Lat_norope:
	s_waitcnt vmcnt(0)
	v_mov_b64_e32 v[64:65], v[16:17]
	v_mov_b64_e32 v[60:61], v[12:13]
	s_andn2_b64 vcc, exec, s[84:85]
	v_mov_b64_e32 v[62:63], v[14:15]
	v_mov_b64_e32 v[58:59], v[10:11]
	s_barrier
	s_cbranch_vccnz .LBB0_726
	v_mov_b64_e32 v[60:61], v[138:139]
	v_mov_b64_e32 v[62:63], v[140:141]
	v_mov_b64_e32 v[64:65], v[142:143]
	v_mov_b64_e32 v[66:67], v[144:145]
	v_mul_f32_e32 v70, v16, v61
	v_mov_b32_e32 v69, v66
	v_mov_b32_e32 v66, v65
	v_mov_b32_e32 v68, v64
	v_pk_mul_f32 v[58:59], v[14:15], v[66:67]
	v_pk_mul_f32 v[64:65], v[10:11], v[66:67]
	v_mul_f32_e32 v66, v12, v60
	v_mul_f32_e32 v72, v16, v60
	v_mul_f32_e32 v74, v12, v61
	v_mov_b32_e32 v60, v13
	v_mov_b32_e32 v61, v17
	v_pk_mul_f32 v[60:61], v[60:61], v[62:63]
	v_pk_fma_f32 v[58:59], v[10:11], v[68:69], v[58:59] neg_lo:[0,0,1] neg_hi:[0,0,1]
	v_mov_b32_e32 v67, v60
	v_mov_b32_e32 v71, v61
	v_pk_add_f32 v[60:61], v[66:67], v[70:71] neg_lo:[0,1] neg_hi:[0,1]
	v_mov_b32_e32 v66, v17
	v_mov_b32_e32 v67, v13
	v_pk_mul_f32 v[62:63], v[66:67], v[62:63]
	s_nop 0
	v_mov_b32_e32 v73, v62
	v_mov_b32_e32 v75, v63
	v_pk_fma_f32 v[62:63], v[14:15], v[68:69], v[64:65]
	v_pk_add_f32 v[64:65], v[72:73], v[74:75]
.LBB0_726:
	v_cvt_pk_bf16_f32 v58, v58, v59
	v_cvt_pk_bf16_f32 v59, v60, v61
	v_cvt_pk_bf16_f32 v60, v62, v63
	s_nop 0
	v_cvt_pk_bf16_f32 v61, v64, v65
	ds_write2_b64 v115, v[58:59], v[60:61] offset1:4
	v_mov_b64_e32 v[64:65], v[24:25]
	v_mov_b64_e32 v[60:61], v[20:21]
	s_and_b64 vcc, exec, s[6:7]
	v_mov_b64_e32 v[62:63], v[22:23]
	v_mov_b64_e32 v[58:59], v[18:19]
	s_cbranch_vccnz .LBB0_728
	v_mov_b64_e32 v[60:61], v[146:147]
	v_mov_b64_e32 v[62:63], v[148:149]
	v_mov_b64_e32 v[64:65], v[150:151]
	v_mov_b64_e32 v[66:67], v[152:153]
	v_mul_f32_e32 v70, v24, v61
	v_mov_b32_e32 v69, v66
	v_mov_b32_e32 v66, v65
	v_mov_b32_e32 v68, v64
	v_pk_mul_f32 v[58:59], v[22:23], v[66:67]
	v_pk_mul_f32 v[64:65], v[18:19], v[66:67]
	v_mul_f32_e32 v66, v20, v60
	v_mul_f32_e32 v72, v24, v60
	v_mul_f32_e32 v74, v20, v61
	v_mov_b32_e32 v60, v21
	v_mov_b32_e32 v61, v25
	v_pk_mul_f32 v[60:61], v[60:61], v[62:63]
	v_pk_fma_f32 v[58:59], v[18:19], v[68:69], v[58:59] neg_lo:[0,0,1] neg_hi:[0,0,1]
	v_mov_b32_e32 v67, v60
	v_mov_b32_e32 v71, v61
	v_pk_add_f32 v[60:61], v[66:67], v[70:71] neg_lo:[0,1] neg_hi:[0,1]
	v_mov_b32_e32 v66, v25
	v_mov_b32_e32 v67, v21
	v_pk_mul_f32 v[62:63], v[66:67], v[62:63]
	s_nop 0
	v_mov_b32_e32 v73, v62
	v_mov_b32_e32 v75, v63
	v_pk_fma_f32 v[62:63], v[22:23], v[68:69], v[64:65]
	v_pk_add_f32 v[64:65], v[72:73], v[74:75]
